# hand-written EpiUp epilogue (packed f32 ops, SGPR-base addressing, no nops), bit-identical; on top of barrier early-invalidate + PRO deferred gain
# speedup vs baseline: 1.0070x; 1.0070x over previous
.LBB0_246:
	v_lshlrev_b32_e32 v0, 3, v179
	v_lshl_add_u32 v0, s18, 5, v0
	s_lshl_b32 s2, s15, 6
	s_lshl_b32 s6, s76, 8
	s_add_i32 s2, s2, s6
	v_add_u32_e32 v174, s2, v177
	v_lshl_add_u32 v186, s40, 7, v0
	v_mul_u32_u24_e32 v175, 0x1600, v174
	v_lshlrev_b32_e32 v188, 2, v186
	v_lshlrev_b32_e32 v174, 2, v174
	v_lshl_add_u32 v175, v186, 1, v175
	global_load_dword v210, v174, s[86:87]
	global_load_dword v212, v174, s[86:87] offset:64
	global_load_dword v214, v174, s[86:87] offset:128
	global_load_dword v216, v174, s[86:87] offset:192
	global_load_dword v218, v174, s[86:87] offset:512
	global_load_dword v220, v174, s[86:87] offset:576
	global_load_dword v222, v174, s[86:87] offset:640
	global_load_dword v224, v174, s[86:87] offset:704
	global_load_dwordx4 v[14:17], v188, s[44:45]
	global_load_dwordx4 v[22:25], v188, s[44:45] offset:16
	global_load_dwordx4 v[26:29], v188, s[78:79]
	global_load_dwordx4 v[74:77], v188, s[78:79] offset:16
	global_load_dwordx4 v[78:81], v188, s[26:27]
	global_load_dwordx4 v[82:85], v188, s[26:27] offset:16
	s_mul_i32 s6, s76, 0x5800
	s_add_u32 s72, s46, s6
	s_addc_u32 s73, s47, 0
	s_sub_u32 s72, s72, 0x26800
	s_subb_u32 s73, s73, 0
	s_mul_i32 s6, s76, 0xb000
	s_add_u32 s76, s68, s6
	s_addc_u32 s77, s69, 0
	v_cmp_lt_i32_e64 s[40:41], 13, v177
	v_cmp_gt_i32_e64 s[42:43], 2, v177
	v_lshlrev_b32_e32 v187, 9, v177
	v_lshl_add_u32 v187, v0, 2, v187
	s_lshl_b32 s2, s15, 10
	s_add_i32 s2, s2, 0x1e400
	v_add_u32_e32 v186, s2, v187
	v_add_u32_e32 v187, 0xfffffc00, v186
	v_mul_u32_u24_e32 v176, 0x2c00, v177
	v_add_u32_e32 v176, v176, v188
	v_mul_u32_u24_e32 v178, 0x5800, v177
	v_add_u32_e32 v178, v178, v188
	v_add_u32_e32 v180, 0x2c00, v178
	s_mov_b32 s98, 0xbfb8aa3b
	s_mov_b32 s99, 0xbfb8aa3b
	s_mov_b32 s92, 1.0
	s_mov_b32 s93, 1.0
	s_waitcnt vmcnt(0)
	v_pk_mul_f32 v[150:151], v[150:151], v[210:211] op_sel_hi:[1,0]
	v_pk_mul_f32 v[152:153], v[152:153], v[210:211] op_sel_hi:[1,0]
	v_pk_mul_f32 v[58:59], v[58:59], v[210:211] op_sel_hi:[1,0]
	v_pk_mul_f32 v[60:61], v[60:61], v[210:211] op_sel_hi:[1,0]
	v_pk_mul_f32 v[142:143], v[142:143], v[210:211] op_sel_hi:[1,0]
	v_pk_mul_f32 v[144:145], v[144:145], v[210:211] op_sel_hi:[1,0]
	v_pk_mul_f32 v[138:139], v[138:139], v[210:211] op_sel_hi:[1,0]
	v_pk_mul_f32 v[140:141], v[140:141], v[210:211] op_sel_hi:[1,0]
	v_pk_mul_f32 v[126:127], v[126:127], v[212:213] op_sel_hi:[1,0]
	v_pk_mul_f32 v[128:129], v[128:129], v[212:213] op_sel_hi:[1,0]
	v_pk_mul_f32 v[122:123], v[122:123], v[212:213] op_sel_hi:[1,0]
	v_pk_mul_f32 v[124:125], v[124:125], v[212:213] op_sel_hi:[1,0]
	v_pk_mul_f32 v[110:111], v[110:111], v[212:213] op_sel_hi:[1,0]
	v_pk_mul_f32 v[112:113], v[112:113], v[212:213] op_sel_hi:[1,0]
	v_pk_mul_f32 v[106:107], v[106:107], v[212:213] op_sel_hi:[1,0]
	v_pk_mul_f32 v[108:109], v[108:109], v[212:213] op_sel_hi:[1,0]
	v_pk_mul_f32 v[118:119], v[118:119], v[214:215] op_sel_hi:[1,0]
	v_pk_mul_f32 v[120:121], v[120:121], v[214:215] op_sel_hi:[1,0]
	v_pk_mul_f32 v[114:115], v[114:115], v[214:215] op_sel_hi:[1,0]
	v_pk_mul_f32 v[116:117], v[116:117], v[214:215] op_sel_hi:[1,0]
	v_pk_mul_f32 v[102:103], v[102:103], v[214:215] op_sel_hi:[1,0]
	v_pk_mul_f32 v[104:105], v[104:105], v[214:215] op_sel_hi:[1,0]
	v_pk_mul_f32 v[98:99], v[98:99], v[214:215] op_sel_hi:[1,0]
	v_pk_mul_f32 v[100:101], v[100:101], v[214:215] op_sel_hi:[1,0]
	v_pk_mul_f32 v[134:135], v[134:135], v[216:217] op_sel_hi:[1,0]
	v_pk_mul_f32 v[136:137], v[136:137], v[216:217] op_sel_hi:[1,0]
	v_pk_mul_f32 v[130:131], v[130:131], v[216:217] op_sel_hi:[1,0]
	v_pk_mul_f32 v[132:133], v[132:133], v[216:217] op_sel_hi:[1,0]
	v_pk_mul_f32 v[94:95], v[94:95], v[216:217] op_sel_hi:[1,0]
	v_pk_mul_f32 v[96:97], v[96:97], v[216:217] op_sel_hi:[1,0]
	v_pk_mul_f32 v[90:91], v[90:91], v[216:217] op_sel_hi:[1,0]
	v_pk_mul_f32 v[92:93], v[92:93], v[216:217] op_sel_hi:[1,0]
	v_pk_mul_f32 v[70:71], v[70:71], v[218:219] op_sel_hi:[1,0]
	v_pk_mul_f32 v[72:73], v[72:73], v[218:219] op_sel_hi:[1,0]
	v_pk_mul_f32 v[66:67], v[66:67], v[218:219] op_sel_hi:[1,0]
	v_pk_mul_f32 v[68:69], v[68:69], v[218:219] op_sel_hi:[1,0]
	v_pk_mul_f32 v[50:51], v[50:51], v[218:219] op_sel_hi:[1,0]
	v_pk_mul_f32 v[52:53], v[52:53], v[218:219] op_sel_hi:[1,0]
	v_pk_mul_f32 v[46:47], v[46:47], v[218:219] op_sel_hi:[1,0]
	v_pk_mul_f32 v[48:49], v[48:49], v[218:219] op_sel_hi:[1,0]
	v_pk_mul_f32 v[62:63], v[62:63], v[220:221] op_sel_hi:[1,0]
	v_pk_mul_f32 v[64:65], v[64:65], v[220:221] op_sel_hi:[1,0]
	v_pk_mul_f32 v[54:55], v[54:55], v[220:221] op_sel_hi:[1,0]
	v_pk_mul_f32 v[56:57], v[56:57], v[220:221] op_sel_hi:[1,0]
	v_pk_mul_f32 v[34:35], v[34:35], v[220:221] op_sel_hi:[1,0]
	v_pk_mul_f32 v[36:37], v[36:37], v[220:221] op_sel_hi:[1,0]
	v_pk_mul_f32 v[30:31], v[30:31], v[220:221] op_sel_hi:[1,0]
	v_pk_mul_f32 v[32:33], v[32:33], v[220:221] op_sel_hi:[1,0]
	v_pk_mul_f32 v[42:43], v[42:43], v[222:223] op_sel_hi:[1,0]
	v_pk_mul_f32 v[44:45], v[44:45], v[222:223] op_sel_hi:[1,0]
	v_pk_mul_f32 v[38:39], v[38:39], v[222:223] op_sel_hi:[1,0]
	v_pk_mul_f32 v[40:41], v[40:41], v[222:223] op_sel_hi:[1,0]
	v_pk_mul_f32 v[18:19], v[18:19], v[222:223] op_sel_hi:[1,0]
	v_pk_mul_f32 v[20:21], v[20:21], v[222:223] op_sel_hi:[1,0]
	v_pk_mul_f32 v[10:11], v[10:11], v[222:223] op_sel_hi:[1,0]
	v_pk_mul_f32 v[12:13], v[12:13], v[222:223] op_sel_hi:[1,0]
	v_pk_mul_f32 v[86:87], v[86:87], v[224:225] op_sel_hi:[1,0]
	v_pk_mul_f32 v[88:89], v[88:89], v[224:225] op_sel_hi:[1,0]
	v_pk_mul_f32 v[146:147], v[146:147], v[224:225] op_sel_hi:[1,0]
	v_pk_mul_f32 v[148:149], v[148:149], v[224:225] op_sel_hi:[1,0]
	v_pk_mul_f32 v[6:7], v[6:7], v[224:225] op_sel_hi:[1,0]
	v_pk_mul_f32 v[8:9], v[8:9], v[224:225] op_sel_hi:[1,0]
	v_pk_mul_f32 v[2:3], v[2:3], v[224:225] op_sel_hi:[1,0]
	v_pk_mul_f32 v[4:5], v[4:5], v[224:225] op_sel_hi:[1,0]
	s_and_saveexec_b64 s[70:71], s[40:41]
	ds_write_b128 v186, v[134:137]
	ds_write_b128 v186, v[130:133] offset:16
	ds_write_b128 v186, v[86:89] offset:2048
	ds_write_b128 v186, v[146:149] offset:2064
	s_cmp_lg_u32 s15, 1
	s_cbranch_scc1 .Lepi_nohg
	global_store_dwordx4 v176, v[86:89], s[72:73]
	global_store_dwordx4 v176, v[146:149], s[72:73] offset:16
.Lepi_nohg:
	s_or_b64 exec, exec, s[70:71]
	s_cmp_lg_u32 s15, 0
	s_cbranch_scc1 .Lepi_nohr
	s_and_saveexec_b64 s[70:71], s[42:43]
	global_store_dwordx4 v178, v[150:153], s[76:77]
	global_store_dwordx4 v178, v[58:61], s[76:77] offset:16
	global_store_dwordx4 v180, v[142:145], s[76:77]
	global_store_dwordx4 v180, v[138:141], s[76:77] offset:16
	s_or_b64 exec, exec, s[70:71]
.Lepi_nohr:
	s_waitcnt lgkmcnt(0)
	s_barrier
	v_cmp_eq_u32_e32 vcc, 0, v177
	v_cndmask_b32_e64 v182, 0, v14, s[42:43]
	v_cndmask_b32_e64 v183, 0, v15, s[42:43]
	v_cndmask_b32_e64 v184, 0, v16, s[42:43]
	v_cndmask_b32_e64 v185, 0, v17, s[42:43]
	v_cndmask_b32_e64 v190, 0, v22, s[42:43]
	v_cndmask_b32_e64 v191, 0, v23, s[42:43]
	v_cndmask_b32_e64 v192, 0, v24, s[42:43]
	v_cndmask_b32_e64 v193, 0, v25, s[42:43]
	v_cndmask_b32_e32 v154, 0, v26, vcc
	v_cndmask_b32_e32 v155, 0, v27, vcc
	v_cndmask_b32_e32 v156, 0, v28, vcc
	v_cndmask_b32_e32 v157, 0, v29, vcc
	v_cndmask_b32_e32 v158, 0, v74, vcc
	v_cndmask_b32_e32 v159, 0, v75, vcc
	v_cndmask_b32_e32 v160, 0, v76, vcc
	v_cndmask_b32_e32 v161, 0, v77, vcc
	v_mov_b64_e32 v[194:195], 0
	v_mov_b64_e32 v[196:197], 0
	v_mov_b64_e32 v[198:199], 0
	v_mov_b64_e32 v[200:201], 0
	s_cmp_lt_i32 s15, 1
	s_cbranch_scc1 .Lepi_gp0
	s_and_saveexec_b64 s[70:71], s[40:41]
	ds_read_b128 v[194:197], v187
	ds_read_b128 v[198:201], v187 offset:16
	s_or_b64 exec, exec, s[70:71]
.Lepi_gp0:
	s_waitcnt lgkmcnt(0)
	s_mov_b64 s[72:73], s[84:85]
	v_pk_mul_f32 v[202:203], v[150:151], v[78:79]
	v_pk_mul_f32 v[204:205], v[152:153], v[80:81]
	v_pk_mul_f32 v[206:207], v[58:59], v[82:83]
	v_pk_mul_f32 v[226:227], v[60:61], v[84:85]
	v_fmac_f32_dpp v202, v150, v26 row_shr:1 row_mask:0xf bank_mask:0xf bound_ctrl:1
	v_fmac_f32_dpp v203, v151, v27 row_shr:1 row_mask:0xf bank_mask:0xf bound_ctrl:1
	v_fmac_f32_dpp v204, v152, v28 row_shr:1 row_mask:0xf bank_mask:0xf bound_ctrl:1
	v_fmac_f32_dpp v205, v153, v29 row_shr:1 row_mask:0xf bank_mask:0xf bound_ctrl:1
	v_fmac_f32_dpp v206, v58, v74 row_shr:1 row_mask:0xf bank_mask:0xf bound_ctrl:1
	v_fmac_f32_dpp v207, v59, v75 row_shr:1 row_mask:0xf bank_mask:0xf bound_ctrl:1
	v_fmac_f32_dpp v226, v60, v76 row_shr:1 row_mask:0xf bank_mask:0xf bound_ctrl:1
	v_fmac_f32_dpp v227, v61, v77 row_shr:1 row_mask:0xf bank_mask:0xf bound_ctrl:1
	v_fmac_f32_dpp v202, v150, v14 row_shr:2 row_mask:0xf bank_mask:0xf bound_ctrl:1
	v_fmac_f32_dpp v203, v151, v15 row_shr:2 row_mask:0xf bank_mask:0xf bound_ctrl:1
	v_fmac_f32_dpp v204, v152, v16 row_shr:2 row_mask:0xf bank_mask:0xf bound_ctrl:1
	v_fmac_f32_dpp v205, v153, v17 row_shr:2 row_mask:0xf bank_mask:0xf bound_ctrl:1
	v_fmac_f32_dpp v206, v58, v22 row_shr:2 row_mask:0xf bank_mask:0xf bound_ctrl:1
	v_fmac_f32_dpp v207, v59, v23 row_shr:2 row_mask:0xf bank_mask:0xf bound_ctrl:1
	v_fmac_f32_dpp v226, v60, v24 row_shr:2 row_mask:0xf bank_mask:0xf bound_ctrl:1
	v_fmac_f32_dpp v227, v61, v25 row_shr:2 row_mask:0xf bank_mask:0xf bound_ctrl:1
	v_fmac_f32_dpp v202, v194, v154 row_ror:1 row_mask:0xf bank_mask:0xf bound_ctrl:1
	v_fmac_f32_dpp v203, v195, v155 row_ror:1 row_mask:0xf bank_mask:0xf bound_ctrl:1
	v_fmac_f32_dpp v204, v196, v156 row_ror:1 row_mask:0xf bank_mask:0xf bound_ctrl:1
	v_fmac_f32_dpp v205, v197, v157 row_ror:1 row_mask:0xf bank_mask:0xf bound_ctrl:1
	v_fmac_f32_dpp v206, v198, v158 row_ror:1 row_mask:0xf bank_mask:0xf bound_ctrl:1
	v_fmac_f32_dpp v207, v199, v159 row_ror:1 row_mask:0xf bank_mask:0xf bound_ctrl:1
	v_fmac_f32_dpp v226, v200, v160 row_ror:1 row_mask:0xf bank_mask:0xf bound_ctrl:1
	v_fmac_f32_dpp v227, v201, v161 row_ror:1 row_mask:0xf bank_mask:0xf bound_ctrl:1
	v_fmac_f32_dpp v202, v194, v182 row_ror:2 row_mask:0xf bank_mask:0xf bound_ctrl:1
	v_fmac_f32_dpp v203, v195, v183 row_ror:2 row_mask:0xf bank_mask:0xf bound_ctrl:1
	v_fmac_f32_dpp v204, v196, v184 row_ror:2 row_mask:0xf bank_mask:0xf bound_ctrl:1
	v_fmac_f32_dpp v205, v197, v185 row_ror:2 row_mask:0xf bank_mask:0xf bound_ctrl:1
	v_fmac_f32_dpp v206, v198, v190 row_ror:2 row_mask:0xf bank_mask:0xf bound_ctrl:1
	v_fmac_f32_dpp v207, v199, v191 row_ror:2 row_mask:0xf bank_mask:0xf bound_ctrl:1
	v_fmac_f32_dpp v226, v200, v192 row_ror:2 row_mask:0xf bank_mask:0xf bound_ctrl:1
	v_fmac_f32_dpp v227, v201, v193 row_ror:2 row_mask:0xf bank_mask:0xf bound_ctrl:1
	v_pk_mul_f32 v[242:243], v[202:203], s[98:99]
	v_pk_mul_f32 v[244:245], v[204:205], s[98:99]
	v_pk_mul_f32 v[246:247], v[206:207], s[98:99]
	v_pk_mul_f32 v[248:249], v[226:227], s[98:99]
	v_exp_f32_e32 v242, v242
	v_exp_f32_e32 v243, v243
	v_exp_f32_e32 v244, v244
	v_exp_f32_e32 v245, v245
	v_exp_f32_e32 v246, v246
	v_exp_f32_e32 v247, v247
	v_exp_f32_e32 v248, v248
	v_exp_f32_e32 v249, v249
	v_pk_add_f32 v[242:243], v[242:243], s[92:93]
	v_pk_add_f32 v[244:245], v[244:245], s[92:93]
	v_pk_add_f32 v[246:247], v[246:247], s[92:93]
	v_pk_add_f32 v[248:249], v[248:249], s[92:93]
	v_rcp_f32_e32 v242, v242
	v_rcp_f32_e32 v243, v243
	v_rcp_f32_e32 v244, v244
	v_rcp_f32_e32 v245, v245
	v_rcp_f32_e32 v246, v246
	v_rcp_f32_e32 v247, v247
	v_rcp_f32_e32 v248, v248
	v_rcp_f32_e32 v249, v249
	v_pk_mul_f32 v[202:203], v[202:203], v[242:243]
	v_pk_mul_f32 v[204:205], v[204:205], v[244:245]
	v_pk_mul_f32 v[206:207], v[206:207], v[246:247]
	v_pk_mul_f32 v[226:227], v[226:227], v[248:249]
	v_pk_mul_f32 v[142:143], v[142:143], v[202:203]
	v_pk_mul_f32 v[144:145], v[144:145], v[204:205]
	v_pk_mul_f32 v[138:139], v[138:139], v[206:207]
	v_pk_mul_f32 v[140:141], v[140:141], v[226:227]
	v_cvt_pk_bf16_f32 v250, v142, v143
	v_cvt_pk_bf16_f32 v251, v144, v145
	v_cvt_pk_bf16_f32 v252, v138, v139
	v_cvt_pk_bf16_f32 v253, v140, v141
	s_mov_b64 s[76:77], exec
	s_cmp_lg_u32 s15, 0
	s_cbranch_scc1 .Lepi_st00
	s_andn2_b64 s[76:77], exec, s[42:43]
.Lepi_st00:
	s_and_saveexec_b64 s[70:71], s[76:77]
	global_store_dwordx4 v175, v[250:253], s[72:73]
	s_or_b64 exec, exec, s[70:71]
	s_add_u32 s72, s84, 0x16000
	s_addc_u32 s73, s85, 0
	v_pk_mul_f32 v[202:203], v[126:127], v[78:79]
	v_pk_mul_f32 v[204:205], v[128:129], v[80:81]
	v_pk_mul_f32 v[206:207], v[122:123], v[82:83]
	v_pk_mul_f32 v[226:227], v[124:125], v[84:85]
	v_fmac_f32_dpp v202, v126, v26 row_shr:1 row_mask:0xf bank_mask:0xf bound_ctrl:1
	v_fmac_f32_dpp v203, v127, v27 row_shr:1 row_mask:0xf bank_mask:0xf bound_ctrl:1
	v_fmac_f32_dpp v204, v128, v28 row_shr:1 row_mask:0xf bank_mask:0xf bound_ctrl:1
	v_fmac_f32_dpp v205, v129, v29 row_shr:1 row_mask:0xf bank_mask:0xf bound_ctrl:1
	v_fmac_f32_dpp v206, v122, v74 row_shr:1 row_mask:0xf bank_mask:0xf bound_ctrl:1
	v_fmac_f32_dpp v207, v123, v75 row_shr:1 row_mask:0xf bank_mask:0xf bound_ctrl:1
	v_fmac_f32_dpp v226, v124, v76 row_shr:1 row_mask:0xf bank_mask:0xf bound_ctrl:1
	v_fmac_f32_dpp v227, v125, v77 row_shr:1 row_mask:0xf bank_mask:0xf bound_ctrl:1
	v_fmac_f32_dpp v202, v126, v14 row_shr:2 row_mask:0xf bank_mask:0xf bound_ctrl:1
	v_fmac_f32_dpp v203, v127, v15 row_shr:2 row_mask:0xf bank_mask:0xf bound_ctrl:1
	v_fmac_f32_dpp v204, v128, v16 row_shr:2 row_mask:0xf bank_mask:0xf bound_ctrl:1
	v_fmac_f32_dpp v205, v129, v17 row_shr:2 row_mask:0xf bank_mask:0xf bound_ctrl:1
	v_fmac_f32_dpp v206, v122, v22 row_shr:2 row_mask:0xf bank_mask:0xf bound_ctrl:1
	v_fmac_f32_dpp v207, v123, v23 row_shr:2 row_mask:0xf bank_mask:0xf bound_ctrl:1
	v_fmac_f32_dpp v226, v124, v24 row_shr:2 row_mask:0xf bank_mask:0xf bound_ctrl:1
	v_fmac_f32_dpp v227, v125, v25 row_shr:2 row_mask:0xf bank_mask:0xf bound_ctrl:1
	v_fmac_f32_dpp v202, v150, v154 row_ror:1 row_mask:0xf bank_mask:0xf bound_ctrl:1
	v_fmac_f32_dpp v203, v151, v155 row_ror:1 row_mask:0xf bank_mask:0xf bound_ctrl:1
	v_fmac_f32_dpp v204, v152, v156 row_ror:1 row_mask:0xf bank_mask:0xf bound_ctrl:1
	v_fmac_f32_dpp v205, v153, v157 row_ror:1 row_mask:0xf bank_mask:0xf bound_ctrl:1
	v_fmac_f32_dpp v206, v58, v158 row_ror:1 row_mask:0xf bank_mask:0xf bound_ctrl:1
	v_fmac_f32_dpp v207, v59, v159 row_ror:1 row_mask:0xf bank_mask:0xf bound_ctrl:1
	v_fmac_f32_dpp v226, v60, v160 row_ror:1 row_mask:0xf bank_mask:0xf bound_ctrl:1
	v_fmac_f32_dpp v227, v61, v161 row_ror:1 row_mask:0xf bank_mask:0xf bound_ctrl:1
	v_fmac_f32_dpp v202, v150, v182 row_ror:2 row_mask:0xf bank_mask:0xf bound_ctrl:1
	v_fmac_f32_dpp v203, v151, v183 row_ror:2 row_mask:0xf bank_mask:0xf bound_ctrl:1
	v_fmac_f32_dpp v204, v152, v184 row_ror:2 row_mask:0xf bank_mask:0xf bound_ctrl:1
	v_fmac_f32_dpp v205, v153, v185 row_ror:2 row_mask:0xf bank_mask:0xf bound_ctrl:1
	v_fmac_f32_dpp v206, v58, v190 row_ror:2 row_mask:0xf bank_mask:0xf bound_ctrl:1
	v_fmac_f32_dpp v207, v59, v191 row_ror:2 row_mask:0xf bank_mask:0xf bound_ctrl:1
	v_fmac_f32_dpp v226, v60, v192 row_ror:2 row_mask:0xf bank_mask:0xf bound_ctrl:1
	v_fmac_f32_dpp v227, v61, v193 row_ror:2 row_mask:0xf bank_mask:0xf bound_ctrl:1
	v_pk_mul_f32 v[242:243], v[202:203], s[98:99]
	v_pk_mul_f32 v[244:245], v[204:205], s[98:99]
	v_pk_mul_f32 v[246:247], v[206:207], s[98:99]
	v_pk_mul_f32 v[248:249], v[226:227], s[98:99]
	v_exp_f32_e32 v242, v242
	v_exp_f32_e32 v243, v243
	v_exp_f32_e32 v244, v244
	v_exp_f32_e32 v245, v245
	v_exp_f32_e32 v246, v246
	v_exp_f32_e32 v247, v247
	v_exp_f32_e32 v248, v248
	v_exp_f32_e32 v249, v249
	v_pk_add_f32 v[242:243], v[242:243], s[92:93]
	v_pk_add_f32 v[244:245], v[244:245], s[92:93]
	v_pk_add_f32 v[246:247], v[246:247], s[92:93]
	v_pk_add_f32 v[248:249], v[248:249], s[92:93]
	v_rcp_f32_e32 v242, v242
	v_rcp_f32_e32 v243, v243
	v_rcp_f32_e32 v244, v244
	v_rcp_f32_e32 v245, v245
	v_rcp_f32_e32 v246, v246
	v_rcp_f32_e32 v247, v247
	v_rcp_f32_e32 v248, v248
	v_rcp_f32_e32 v249, v249
	v_pk_mul_f32 v[202:203], v[202:203], v[242:243]
	v_pk_mul_f32 v[204:205], v[204:205], v[244:245]
	v_pk_mul_f32 v[206:207], v[206:207], v[246:247]
	v_pk_mul_f32 v[226:227], v[226:227], v[248:249]
	v_pk_mul_f32 v[110:111], v[110:111], v[202:203]
	v_pk_mul_f32 v[112:113], v[112:113], v[204:205]
	v_pk_mul_f32 v[106:107], v[106:107], v[206:207]
	v_pk_mul_f32 v[108:109], v[108:109], v[226:227]
	v_cvt_pk_bf16_f32 v250, v110, v111
	v_cvt_pk_bf16_f32 v251, v112, v113
	v_cvt_pk_bf16_f32 v252, v106, v107
	v_cvt_pk_bf16_f32 v253, v108, v109
	global_store_dwordx4 v175, v[250:253], s[72:73]
	s_add_u32 s72, s84, 0x2c000
	s_addc_u32 s73, s85, 0
	v_pk_mul_f32 v[202:203], v[118:119], v[78:79]
	v_pk_mul_f32 v[204:205], v[120:121], v[80:81]
	v_pk_mul_f32 v[206:207], v[114:115], v[82:83]
	v_pk_mul_f32 v[226:227], v[116:117], v[84:85]
	v_fmac_f32_dpp v202, v118, v26 row_shr:1 row_mask:0xf bank_mask:0xf bound_ctrl:1
	v_fmac_f32_dpp v203, v119, v27 row_shr:1 row_mask:0xf bank_mask:0xf bound_ctrl:1
	v_fmac_f32_dpp v204, v120, v28 row_shr:1 row_mask:0xf bank_mask:0xf bound_ctrl:1
	v_fmac_f32_dpp v205, v121, v29 row_shr:1 row_mask:0xf bank_mask:0xf bound_ctrl:1
	v_fmac_f32_dpp v206, v114, v74 row_shr:1 row_mask:0xf bank_mask:0xf bound_ctrl:1
	v_fmac_f32_dpp v207, v115, v75 row_shr:1 row_mask:0xf bank_mask:0xf bound_ctrl:1
	v_fmac_f32_dpp v226, v116, v76 row_shr:1 row_mask:0xf bank_mask:0xf bound_ctrl:1
	v_fmac_f32_dpp v227, v117, v77 row_shr:1 row_mask:0xf bank_mask:0xf bound_ctrl:1
	v_fmac_f32_dpp v202, v118, v14 row_shr:2 row_mask:0xf bank_mask:0xf bound_ctrl:1
	v_fmac_f32_dpp v203, v119, v15 row_shr:2 row_mask:0xf bank_mask:0xf bound_ctrl:1
	v_fmac_f32_dpp v204, v120, v16 row_shr:2 row_mask:0xf bank_mask:0xf bound_ctrl:1
	v_fmac_f32_dpp v205, v121, v17 row_shr:2 row_mask:0xf bank_mask:0xf bound_ctrl:1
	v_fmac_f32_dpp v206, v114, v22 row_shr:2 row_mask:0xf bank_mask:0xf bound_ctrl:1
	v_fmac_f32_dpp v207, v115, v23 row_shr:2 row_mask:0xf bank_mask:0xf bound_ctrl:1
	v_fmac_f32_dpp v226, v116, v24 row_shr:2 row_mask:0xf bank_mask:0xf bound_ctrl:1
	v_fmac_f32_dpp v227, v117, v25 row_shr:2 row_mask:0xf bank_mask:0xf bound_ctrl:1
	v_fmac_f32_dpp v202, v126, v154 row_ror:1 row_mask:0xf bank_mask:0xf bound_ctrl:1
	v_fmac_f32_dpp v203, v127, v155 row_ror:1 row_mask:0xf bank_mask:0xf bound_ctrl:1
	v_fmac_f32_dpp v204, v128, v156 row_ror:1 row_mask:0xf bank_mask:0xf bound_ctrl:1
	v_fmac_f32_dpp v205, v129, v157 row_ror:1 row_mask:0xf bank_mask:0xf bound_ctrl:1
	v_fmac_f32_dpp v206, v122, v158 row_ror:1 row_mask:0xf bank_mask:0xf bound_ctrl:1
	v_fmac_f32_dpp v207, v123, v159 row_ror:1 row_mask:0xf bank_mask:0xf bound_ctrl:1
	v_fmac_f32_dpp v226, v124, v160 row_ror:1 row_mask:0xf bank_mask:0xf bound_ctrl:1
	v_fmac_f32_dpp v227, v125, v161 row_ror:1 row_mask:0xf bank_mask:0xf bound_ctrl:1
	v_fmac_f32_dpp v202, v126, v182 row_ror:2 row_mask:0xf bank_mask:0xf bound_ctrl:1
	v_fmac_f32_dpp v203, v127, v183 row_ror:2 row_mask:0xf bank_mask:0xf bound_ctrl:1
	v_fmac_f32_dpp v204, v128, v184 row_ror:2 row_mask:0xf bank_mask:0xf bound_ctrl:1
	v_fmac_f32_dpp v205, v129, v185 row_ror:2 row_mask:0xf bank_mask:0xf bound_ctrl:1
	v_fmac_f32_dpp v206, v122, v190 row_ror:2 row_mask:0xf bank_mask:0xf bound_ctrl:1
	v_fmac_f32_dpp v207, v123, v191 row_ror:2 row_mask:0xf bank_mask:0xf bound_ctrl:1
	v_fmac_f32_dpp v226, v124, v192 row_ror:2 row_mask:0xf bank_mask:0xf bound_ctrl:1
	v_fmac_f32_dpp v227, v125, v193 row_ror:2 row_mask:0xf bank_mask:0xf bound_ctrl:1
	v_pk_mul_f32 v[242:243], v[202:203], s[98:99]
	v_pk_mul_f32 v[244:245], v[204:205], s[98:99]
	v_pk_mul_f32 v[246:247], v[206:207], s[98:99]
	v_pk_mul_f32 v[248:249], v[226:227], s[98:99]
	v_exp_f32_e32 v242, v242
	v_exp_f32_e32 v243, v243
	v_exp_f32_e32 v244, v244
	v_exp_f32_e32 v245, v245
	v_exp_f32_e32 v246, v246
	v_exp_f32_e32 v247, v247
	v_exp_f32_e32 v248, v248
	v_exp_f32_e32 v249, v249
	v_pk_add_f32 v[242:243], v[242:243], s[92:93]
	v_pk_add_f32 v[244:245], v[244:245], s[92:93]
	v_pk_add_f32 v[246:247], v[246:247], s[92:93]
	v_pk_add_f32 v[248:249], v[248:249], s[92:93]
	v_rcp_f32_e32 v242, v242
	v_rcp_f32_e32 v243, v243
	v_rcp_f32_e32 v244, v244
	v_rcp_f32_e32 v245, v245
	v_rcp_f32_e32 v246, v246
	v_rcp_f32_e32 v247, v247
	v_rcp_f32_e32 v248, v248
	v_rcp_f32_e32 v249, v249
	v_pk_mul_f32 v[202:203], v[202:203], v[242:243]
	v_pk_mul_f32 v[204:205], v[204:205], v[244:245]
	v_pk_mul_f32 v[206:207], v[206:207], v[246:247]
	v_pk_mul_f32 v[226:227], v[226:227], v[248:249]
	v_pk_mul_f32 v[102:103], v[102:103], v[202:203]
	v_pk_mul_f32 v[104:105], v[104:105], v[204:205]
	v_pk_mul_f32 v[98:99], v[98:99], v[206:207]
	v_pk_mul_f32 v[100:101], v[100:101], v[226:227]
	v_cvt_pk_bf16_f32 v250, v102, v103
	v_cvt_pk_bf16_f32 v251, v104, v105
	v_cvt_pk_bf16_f32 v252, v98, v99
	v_cvt_pk_bf16_f32 v253, v100, v101
	global_store_dwordx4 v175, v[250:253], s[72:73]
	s_add_u32 s72, s84, 0x42000
	s_addc_u32 s73, s85, 0
	v_pk_mul_f32 v[202:203], v[134:135], v[78:79]
	v_pk_mul_f32 v[204:205], v[136:137], v[80:81]
	v_pk_mul_f32 v[206:207], v[130:131], v[82:83]
	v_pk_mul_f32 v[226:227], v[132:133], v[84:85]
	v_fmac_f32_dpp v202, v134, v26 row_shr:1 row_mask:0xf bank_mask:0xf bound_ctrl:1
	v_fmac_f32_dpp v203, v135, v27 row_shr:1 row_mask:0xf bank_mask:0xf bound_ctrl:1
	v_fmac_f32_dpp v204, v136, v28 row_shr:1 row_mask:0xf bank_mask:0xf bound_ctrl:1
	v_fmac_f32_dpp v205, v137, v29 row_shr:1 row_mask:0xf bank_mask:0xf bound_ctrl:1
	v_fmac_f32_dpp v206, v130, v74 row_shr:1 row_mask:0xf bank_mask:0xf bound_ctrl:1
	v_fmac_f32_dpp v207, v131, v75 row_shr:1 row_mask:0xf bank_mask:0xf bound_ctrl:1
	v_fmac_f32_dpp v226, v132, v76 row_shr:1 row_mask:0xf bank_mask:0xf bound_ctrl:1
	v_fmac_f32_dpp v227, v133, v77 row_shr:1 row_mask:0xf bank_mask:0xf bound_ctrl:1
	v_fmac_f32_dpp v202, v134, v14 row_shr:2 row_mask:0xf bank_mask:0xf bound_ctrl:1
	v_fmac_f32_dpp v203, v135, v15 row_shr:2 row_mask:0xf bank_mask:0xf bound_ctrl:1
	v_fmac_f32_dpp v204, v136, v16 row_shr:2 row_mask:0xf bank_mask:0xf bound_ctrl:1
	v_fmac_f32_dpp v205, v137, v17 row_shr:2 row_mask:0xf bank_mask:0xf bound_ctrl:1
	v_fmac_f32_dpp v206, v130, v22 row_shr:2 row_mask:0xf bank_mask:0xf bound_ctrl:1
	v_fmac_f32_dpp v207, v131, v23 row_shr:2 row_mask:0xf bank_mask:0xf bound_ctrl:1
	v_fmac_f32_dpp v226, v132, v24 row_shr:2 row_mask:0xf bank_mask:0xf bound_ctrl:1
	v_fmac_f32_dpp v227, v133, v25 row_shr:2 row_mask:0xf bank_mask:0xf bound_ctrl:1
	v_fmac_f32_dpp v202, v118, v154 row_ror:1 row_mask:0xf bank_mask:0xf bound_ctrl:1
	v_fmac_f32_dpp v203, v119, v155 row_ror:1 row_mask:0xf bank_mask:0xf bound_ctrl:1
	v_fmac_f32_dpp v204, v120, v156 row_ror:1 row_mask:0xf bank_mask:0xf bound_ctrl:1
	v_fmac_f32_dpp v205, v121, v157 row_ror:1 row_mask:0xf bank_mask:0xf bound_ctrl:1
	v_fmac_f32_dpp v206, v114, v158 row_ror:1 row_mask:0xf bank_mask:0xf bound_ctrl:1
	v_fmac_f32_dpp v207, v115, v159 row_ror:1 row_mask:0xf bank_mask:0xf bound_ctrl:1
	v_fmac_f32_dpp v226, v116, v160 row_ror:1 row_mask:0xf bank_mask:0xf bound_ctrl:1
	v_fmac_f32_dpp v227, v117, v161 row_ror:1 row_mask:0xf bank_mask:0xf bound_ctrl:1
	v_fmac_f32_dpp v202, v118, v182 row_ror:2 row_mask:0xf bank_mask:0xf bound_ctrl:1
	v_fmac_f32_dpp v203, v119, v183 row_ror:2 row_mask:0xf bank_mask:0xf bound_ctrl:1
	v_fmac_f32_dpp v204, v120, v184 row_ror:2 row_mask:0xf bank_mask:0xf bound_ctrl:1
	v_fmac_f32_dpp v205, v121, v185 row_ror:2 row_mask:0xf bank_mask:0xf bound_ctrl:1
	v_fmac_f32_dpp v206, v114, v190 row_ror:2 row_mask:0xf bank_mask:0xf bound_ctrl:1
	v_fmac_f32_dpp v207, v115, v191 row_ror:2 row_mask:0xf bank_mask:0xf bound_ctrl:1
	v_fmac_f32_dpp v226, v116, v192 row_ror:2 row_mask:0xf bank_mask:0xf bound_ctrl:1
	v_fmac_f32_dpp v227, v117, v193 row_ror:2 row_mask:0xf bank_mask:0xf bound_ctrl:1
	v_pk_mul_f32 v[242:243], v[202:203], s[98:99]
	v_pk_mul_f32 v[244:245], v[204:205], s[98:99]
	v_pk_mul_f32 v[246:247], v[206:207], s[98:99]
	v_pk_mul_f32 v[248:249], v[226:227], s[98:99]
	v_exp_f32_e32 v242, v242
	v_exp_f32_e32 v243, v243
	v_exp_f32_e32 v244, v244
	v_exp_f32_e32 v245, v245
	v_exp_f32_e32 v246, v246
	v_exp_f32_e32 v247, v247
	v_exp_f32_e32 v248, v248
	v_exp_f32_e32 v249, v249
	v_pk_add_f32 v[242:243], v[242:243], s[92:93]
	v_pk_add_f32 v[244:245], v[244:245], s[92:93]
	v_pk_add_f32 v[246:247], v[246:247], s[92:93]
	v_pk_add_f32 v[248:249], v[248:249], s[92:93]
	v_rcp_f32_e32 v242, v242
	v_rcp_f32_e32 v243, v243
	v_rcp_f32_e32 v244, v244
	v_rcp_f32_e32 v245, v245
	v_rcp_f32_e32 v246, v246
	v_rcp_f32_e32 v247, v247
	v_rcp_f32_e32 v248, v248
	v_rcp_f32_e32 v249, v249
	v_pk_mul_f32 v[202:203], v[202:203], v[242:243]
	v_pk_mul_f32 v[204:205], v[204:205], v[244:245]
	v_pk_mul_f32 v[206:207], v[206:207], v[246:247]
	v_pk_mul_f32 v[226:227], v[226:227], v[248:249]
	v_pk_mul_f32 v[94:95], v[94:95], v[202:203]
	v_pk_mul_f32 v[96:97], v[96:97], v[204:205]
	v_pk_mul_f32 v[90:91], v[90:91], v[206:207]
	v_pk_mul_f32 v[92:93], v[92:93], v[226:227]
	v_cvt_pk_bf16_f32 v250, v94, v95
	v_cvt_pk_bf16_f32 v251, v96, v97
	v_cvt_pk_bf16_f32 v252, v90, v91
	v_cvt_pk_bf16_f32 v253, v92, v93
	global_store_dwordx4 v175, v[250:253], s[72:73]
	v_mov_b64_e32 v[194:195], 0
	v_mov_b64_e32 v[196:197], 0
	v_mov_b64_e32 v[198:199], 0
	v_mov_b64_e32 v[200:201], 0
	s_and_saveexec_b64 s[70:71], s[40:41]
	ds_read_b128 v[194:197], v187 offset:2048
	ds_read_b128 v[198:201], v187 offset:2064
	s_or_b64 exec, exec, s[70:71]
	s_waitcnt lgkmcnt(0)
	s_add_u32 s72, s84, 0xb0000
	s_addc_u32 s73, s85, 0
	v_pk_mul_f32 v[202:203], v[70:71], v[78:79]
	v_pk_mul_f32 v[204:205], v[72:73], v[80:81]
	v_pk_mul_f32 v[206:207], v[66:67], v[82:83]
	v_pk_mul_f32 v[226:227], v[68:69], v[84:85]
	v_fmac_f32_dpp v202, v70, v26 row_shr:1 row_mask:0xf bank_mask:0xf bound_ctrl:1
	v_fmac_f32_dpp v203, v71, v27 row_shr:1 row_mask:0xf bank_mask:0xf bound_ctrl:1
	v_fmac_f32_dpp v204, v72, v28 row_shr:1 row_mask:0xf bank_mask:0xf bound_ctrl:1
	v_fmac_f32_dpp v205, v73, v29 row_shr:1 row_mask:0xf bank_mask:0xf bound_ctrl:1
	v_fmac_f32_dpp v206, v66, v74 row_shr:1 row_mask:0xf bank_mask:0xf bound_ctrl:1
	v_fmac_f32_dpp v207, v67, v75 row_shr:1 row_mask:0xf bank_mask:0xf bound_ctrl:1
	v_fmac_f32_dpp v226, v68, v76 row_shr:1 row_mask:0xf bank_mask:0xf bound_ctrl:1
	v_fmac_f32_dpp v227, v69, v77 row_shr:1 row_mask:0xf bank_mask:0xf bound_ctrl:1
	v_fmac_f32_dpp v202, v70, v14 row_shr:2 row_mask:0xf bank_mask:0xf bound_ctrl:1
	v_fmac_f32_dpp v203, v71, v15 row_shr:2 row_mask:0xf bank_mask:0xf bound_ctrl:1
	v_fmac_f32_dpp v204, v72, v16 row_shr:2 row_mask:0xf bank_mask:0xf bound_ctrl:1
	v_fmac_f32_dpp v205, v73, v17 row_shr:2 row_mask:0xf bank_mask:0xf bound_ctrl:1
	v_fmac_f32_dpp v206, v66, v22 row_shr:2 row_mask:0xf bank_mask:0xf bound_ctrl:1
	v_fmac_f32_dpp v207, v67, v23 row_shr:2 row_mask:0xf bank_mask:0xf bound_ctrl:1
	v_fmac_f32_dpp v226, v68, v24 row_shr:2 row_mask:0xf bank_mask:0xf bound_ctrl:1
	v_fmac_f32_dpp v227, v69, v25 row_shr:2 row_mask:0xf bank_mask:0xf bound_ctrl:1
	v_fmac_f32_dpp v202, v194, v154 row_ror:1 row_mask:0xf bank_mask:0xf bound_ctrl:1
	v_fmac_f32_dpp v203, v195, v155 row_ror:1 row_mask:0xf bank_mask:0xf bound_ctrl:1
	v_fmac_f32_dpp v204, v196, v156 row_ror:1 row_mask:0xf bank_mask:0xf bound_ctrl:1
	v_fmac_f32_dpp v205, v197, v157 row_ror:1 row_mask:0xf bank_mask:0xf bound_ctrl:1
	v_fmac_f32_dpp v206, v198, v158 row_ror:1 row_mask:0xf bank_mask:0xf bound_ctrl:1
	v_fmac_f32_dpp v207, v199, v159 row_ror:1 row_mask:0xf bank_mask:0xf bound_ctrl:1
	v_fmac_f32_dpp v226, v200, v160 row_ror:1 row_mask:0xf bank_mask:0xf bound_ctrl:1
	v_fmac_f32_dpp v227, v201, v161 row_ror:1 row_mask:0xf bank_mask:0xf bound_ctrl:1
	v_fmac_f32_dpp v202, v194, v182 row_ror:2 row_mask:0xf bank_mask:0xf bound_ctrl:1
	v_fmac_f32_dpp v203, v195, v183 row_ror:2 row_mask:0xf bank_mask:0xf bound_ctrl:1
	v_fmac_f32_dpp v204, v196, v184 row_ror:2 row_mask:0xf bank_mask:0xf bound_ctrl:1
	v_fmac_f32_dpp v205, v197, v185 row_ror:2 row_mask:0xf bank_mask:0xf bound_ctrl:1
	v_fmac_f32_dpp v206, v198, v190 row_ror:2 row_mask:0xf bank_mask:0xf bound_ctrl:1
	v_fmac_f32_dpp v207, v199, v191 row_ror:2 row_mask:0xf bank_mask:0xf bound_ctrl:1
	v_fmac_f32_dpp v226, v200, v192 row_ror:2 row_mask:0xf bank_mask:0xf bound_ctrl:1
	v_fmac_f32_dpp v227, v201, v193 row_ror:2 row_mask:0xf bank_mask:0xf bound_ctrl:1
	v_pk_mul_f32 v[242:243], v[202:203], s[98:99]
	v_pk_mul_f32 v[244:245], v[204:205], s[98:99]
	v_pk_mul_f32 v[246:247], v[206:207], s[98:99]
	v_pk_mul_f32 v[248:249], v[226:227], s[98:99]
	v_exp_f32_e32 v242, v242
	v_exp_f32_e32 v243, v243
	v_exp_f32_e32 v244, v244
	v_exp_f32_e32 v245, v245
	v_exp_f32_e32 v246, v246
	v_exp_f32_e32 v247, v247
	v_exp_f32_e32 v248, v248
	v_exp_f32_e32 v249, v249
	v_pk_add_f32 v[242:243], v[242:243], s[92:93]
	v_pk_add_f32 v[244:245], v[244:245], s[92:93]
	v_pk_add_f32 v[246:247], v[246:247], s[92:93]
	v_pk_add_f32 v[248:249], v[248:249], s[92:93]
	v_rcp_f32_e32 v242, v242
	v_rcp_f32_e32 v243, v243
	v_rcp_f32_e32 v244, v244
	v_rcp_f32_e32 v245, v245
	v_rcp_f32_e32 v246, v246
	v_rcp_f32_e32 v247, v247
	v_rcp_f32_e32 v248, v248
	v_rcp_f32_e32 v249, v249
	v_pk_mul_f32 v[202:203], v[202:203], v[242:243]
	v_pk_mul_f32 v[204:205], v[204:205], v[244:245]
	v_pk_mul_f32 v[206:207], v[206:207], v[246:247]
	v_pk_mul_f32 v[226:227], v[226:227], v[248:249]
	v_pk_mul_f32 v[50:51], v[50:51], v[202:203]
	v_pk_mul_f32 v[52:53], v[52:53], v[204:205]
	v_pk_mul_f32 v[46:47], v[46:47], v[206:207]
	v_pk_mul_f32 v[48:49], v[48:49], v[226:227]
	v_cvt_pk_bf16_f32 v250, v50, v51
	v_cvt_pk_bf16_f32 v251, v52, v53
	v_cvt_pk_bf16_f32 v252, v46, v47
	v_cvt_pk_bf16_f32 v253, v48, v49
	global_store_dwordx4 v175, v[250:253], s[72:73]
	s_add_u32 s72, s84, 0xc6000
	s_addc_u32 s73, s85, 0
	v_pk_mul_f32 v[202:203], v[62:63], v[78:79]
	v_pk_mul_f32 v[204:205], v[64:65], v[80:81]
	v_pk_mul_f32 v[206:207], v[54:55], v[82:83]
	v_pk_mul_f32 v[226:227], v[56:57], v[84:85]
	v_fmac_f32_dpp v202, v62, v26 row_shr:1 row_mask:0xf bank_mask:0xf bound_ctrl:1
	v_fmac_f32_dpp v203, v63, v27 row_shr:1 row_mask:0xf bank_mask:0xf bound_ctrl:1
	v_fmac_f32_dpp v204, v64, v28 row_shr:1 row_mask:0xf bank_mask:0xf bound_ctrl:1
	v_fmac_f32_dpp v205, v65, v29 row_shr:1 row_mask:0xf bank_mask:0xf bound_ctrl:1
	v_fmac_f32_dpp v206, v54, v74 row_shr:1 row_mask:0xf bank_mask:0xf bound_ctrl:1
	v_fmac_f32_dpp v207, v55, v75 row_shr:1 row_mask:0xf bank_mask:0xf bound_ctrl:1
	v_fmac_f32_dpp v226, v56, v76 row_shr:1 row_mask:0xf bank_mask:0xf bound_ctrl:1
	v_fmac_f32_dpp v227, v57, v77 row_shr:1 row_mask:0xf bank_mask:0xf bound_ctrl:1
	v_fmac_f32_dpp v202, v62, v14 row_shr:2 row_mask:0xf bank_mask:0xf bound_ctrl:1
	v_fmac_f32_dpp v203, v63, v15 row_shr:2 row_mask:0xf bank_mask:0xf bound_ctrl:1
	v_fmac_f32_dpp v204, v64, v16 row_shr:2 row_mask:0xf bank_mask:0xf bound_ctrl:1
	v_fmac_f32_dpp v205, v65, v17 row_shr:2 row_mask:0xf bank_mask:0xf bound_ctrl:1
	v_fmac_f32_dpp v206, v54, v22 row_shr:2 row_mask:0xf bank_mask:0xf bound_ctrl:1
	v_fmac_f32_dpp v207, v55, v23 row_shr:2 row_mask:0xf bank_mask:0xf bound_ctrl:1
	v_fmac_f32_dpp v226, v56, v24 row_shr:2 row_mask:0xf bank_mask:0xf bound_ctrl:1
	v_fmac_f32_dpp v227, v57, v25 row_shr:2 row_mask:0xf bank_mask:0xf bound_ctrl:1
	v_fmac_f32_dpp v202, v70, v154 row_ror:1 row_mask:0xf bank_mask:0xf bound_ctrl:1
	v_fmac_f32_dpp v203, v71, v155 row_ror:1 row_mask:0xf bank_mask:0xf bound_ctrl:1
	v_fmac_f32_dpp v204, v72, v156 row_ror:1 row_mask:0xf bank_mask:0xf bound_ctrl:1
	v_fmac_f32_dpp v205, v73, v157 row_ror:1 row_mask:0xf bank_mask:0xf bound_ctrl:1
	v_fmac_f32_dpp v206, v66, v158 row_ror:1 row_mask:0xf bank_mask:0xf bound_ctrl:1
	v_fmac_f32_dpp v207, v67, v159 row_ror:1 row_mask:0xf bank_mask:0xf bound_ctrl:1
	v_fmac_f32_dpp v226, v68, v160 row_ror:1 row_mask:0xf bank_mask:0xf bound_ctrl:1
	v_fmac_f32_dpp v227, v69, v161 row_ror:1 row_mask:0xf bank_mask:0xf bound_ctrl:1
	v_fmac_f32_dpp v202, v70, v182 row_ror:2 row_mask:0xf bank_mask:0xf bound_ctrl:1
	v_fmac_f32_dpp v203, v71, v183 row_ror:2 row_mask:0xf bank_mask:0xf bound_ctrl:1
	v_fmac_f32_dpp v204, v72, v184 row_ror:2 row_mask:0xf bank_mask:0xf bound_ctrl:1
	v_fmac_f32_dpp v205, v73, v185 row_ror:2 row_mask:0xf bank_mask:0xf bound_ctrl:1
	v_fmac_f32_dpp v206, v66, v190 row_ror:2 row_mask:0xf bank_mask:0xf bound_ctrl:1
	v_fmac_f32_dpp v207, v67, v191 row_ror:2 row_mask:0xf bank_mask:0xf bound_ctrl:1
	v_fmac_f32_dpp v226, v68, v192 row_ror:2 row_mask:0xf bank_mask:0xf bound_ctrl:1
	v_fmac_f32_dpp v227, v69, v193 row_ror:2 row_mask:0xf bank_mask:0xf bound_ctrl:1
	v_pk_mul_f32 v[242:243], v[202:203], s[98:99]
	v_pk_mul_f32 v[244:245], v[204:205], s[98:99]
	v_pk_mul_f32 v[246:247], v[206:207], s[98:99]
	v_pk_mul_f32 v[248:249], v[226:227], s[98:99]
	v_exp_f32_e32 v242, v242
	v_exp_f32_e32 v243, v243
	v_exp_f32_e32 v244, v244
	v_exp_f32_e32 v245, v245
	v_exp_f32_e32 v246, v246
	v_exp_f32_e32 v247, v247
	v_exp_f32_e32 v248, v248
	v_exp_f32_e32 v249, v249
	v_pk_add_f32 v[242:243], v[242:243], s[92:93]
	v_pk_add_f32 v[244:245], v[244:245], s[92:93]
	v_pk_add_f32 v[246:247], v[246:247], s[92:93]
	v_pk_add_f32 v[248:249], v[248:249], s[92:93]
	v_rcp_f32_e32 v242, v242
	v_rcp_f32_e32 v243, v243
	v_rcp_f32_e32 v244, v244
	v_rcp_f32_e32 v245, v245
	v_rcp_f32_e32 v246, v246
	v_rcp_f32_e32 v247, v247
	v_rcp_f32_e32 v248, v248
	v_rcp_f32_e32 v249, v249
	v_pk_mul_f32 v[202:203], v[202:203], v[242:243]
	v_pk_mul_f32 v[204:205], v[204:205], v[244:245]
	v_pk_mul_f32 v[206:207], v[206:207], v[246:247]
	v_pk_mul_f32 v[226:227], v[226:227], v[248:249]
	v_pk_mul_f32 v[34:35], v[34:35], v[202:203]
	v_pk_mul_f32 v[36:37], v[36:37], v[204:205]
	v_pk_mul_f32 v[30:31], v[30:31], v[206:207]
	v_pk_mul_f32 v[32:33], v[32:33], v[226:227]
	v_cvt_pk_bf16_f32 v250, v34, v35
	v_cvt_pk_bf16_f32 v251, v36, v37
	v_cvt_pk_bf16_f32 v252, v30, v31
	v_cvt_pk_bf16_f32 v253, v32, v33
	global_store_dwordx4 v175, v[250:253], s[72:73]
	s_add_u32 s72, s84, 0xdc000
	s_addc_u32 s73, s85, 0
	v_pk_mul_f32 v[202:203], v[42:43], v[78:79]
	v_pk_mul_f32 v[204:205], v[44:45], v[80:81]
	v_pk_mul_f32 v[206:207], v[38:39], v[82:83]
	v_pk_mul_f32 v[226:227], v[40:41], v[84:85]
	v_fmac_f32_dpp v202, v42, v26 row_shr:1 row_mask:0xf bank_mask:0xf bound_ctrl:1
	v_fmac_f32_dpp v203, v43, v27 row_shr:1 row_mask:0xf bank_mask:0xf bound_ctrl:1
	v_fmac_f32_dpp v204, v44, v28 row_shr:1 row_mask:0xf bank_mask:0xf bound_ctrl:1
	v_fmac_f32_dpp v205, v45, v29 row_shr:1 row_mask:0xf bank_mask:0xf bound_ctrl:1
	v_fmac_f32_dpp v206, v38, v74 row_shr:1 row_mask:0xf bank_mask:0xf bound_ctrl:1
	v_fmac_f32_dpp v207, v39, v75 row_shr:1 row_mask:0xf bank_mask:0xf bound_ctrl:1
	v_fmac_f32_dpp v226, v40, v76 row_shr:1 row_mask:0xf bank_mask:0xf bound_ctrl:1
	v_fmac_f32_dpp v227, v41, v77 row_shr:1 row_mask:0xf bank_mask:0xf bound_ctrl:1
	v_fmac_f32_dpp v202, v42, v14 row_shr:2 row_mask:0xf bank_mask:0xf bound_ctrl:1
	v_fmac_f32_dpp v203, v43, v15 row_shr:2 row_mask:0xf bank_mask:0xf bound_ctrl:1
	v_fmac_f32_dpp v204, v44, v16 row_shr:2 row_mask:0xf bank_mask:0xf bound_ctrl:1
	v_fmac_f32_dpp v205, v45, v17 row_shr:2 row_mask:0xf bank_mask:0xf bound_ctrl:1
	v_fmac_f32_dpp v206, v38, v22 row_shr:2 row_mask:0xf bank_mask:0xf bound_ctrl:1
	v_fmac_f32_dpp v207, v39, v23 row_shr:2 row_mask:0xf bank_mask:0xf bound_ctrl:1
	v_fmac_f32_dpp v226, v40, v24 row_shr:2 row_mask:0xf bank_mask:0xf bound_ctrl:1
	v_fmac_f32_dpp v227, v41, v25 row_shr:2 row_mask:0xf bank_mask:0xf bound_ctrl:1
	v_fmac_f32_dpp v202, v62, v154 row_ror:1 row_mask:0xf bank_mask:0xf bound_ctrl:1
	v_fmac_f32_dpp v203, v63, v155 row_ror:1 row_mask:0xf bank_mask:0xf bound_ctrl:1
	v_fmac_f32_dpp v204, v64, v156 row_ror:1 row_mask:0xf bank_mask:0xf bound_ctrl:1
	v_fmac_f32_dpp v205, v65, v157 row_ror:1 row_mask:0xf bank_mask:0xf bound_ctrl:1
	v_fmac_f32_dpp v206, v54, v158 row_ror:1 row_mask:0xf bank_mask:0xf bound_ctrl:1
	v_fmac_f32_dpp v207, v55, v159 row_ror:1 row_mask:0xf bank_mask:0xf bound_ctrl:1
	v_fmac_f32_dpp v226, v56, v160 row_ror:1 row_mask:0xf bank_mask:0xf bound_ctrl:1
	v_fmac_f32_dpp v227, v57, v161 row_ror:1 row_mask:0xf bank_mask:0xf bound_ctrl:1
	v_fmac_f32_dpp v202, v62, v182 row_ror:2 row_mask:0xf bank_mask:0xf bound_ctrl:1
	v_fmac_f32_dpp v203, v63, v183 row_ror:2 row_mask:0xf bank_mask:0xf bound_ctrl:1
	v_fmac_f32_dpp v204, v64, v184 row_ror:2 row_mask:0xf bank_mask:0xf bound_ctrl:1
	v_fmac_f32_dpp v205, v65, v185 row_ror:2 row_mask:0xf bank_mask:0xf bound_ctrl:1
	v_fmac_f32_dpp v206, v54, v190 row_ror:2 row_mask:0xf bank_mask:0xf bound_ctrl:1
	v_fmac_f32_dpp v207, v55, v191 row_ror:2 row_mask:0xf bank_mask:0xf bound_ctrl:1
	v_fmac_f32_dpp v226, v56, v192 row_ror:2 row_mask:0xf bank_mask:0xf bound_ctrl:1
	v_fmac_f32_dpp v227, v57, v193 row_ror:2 row_mask:0xf bank_mask:0xf bound_ctrl:1
	v_pk_mul_f32 v[242:243], v[202:203], s[98:99]
	v_pk_mul_f32 v[244:245], v[204:205], s[98:99]
	v_pk_mul_f32 v[246:247], v[206:207], s[98:99]
	v_pk_mul_f32 v[248:249], v[226:227], s[98:99]
	v_exp_f32_e32 v242, v242
	v_exp_f32_e32 v243, v243
	v_exp_f32_e32 v244, v244
	v_exp_f32_e32 v245, v245
	v_exp_f32_e32 v246, v246
	v_exp_f32_e32 v247, v247
	v_exp_f32_e32 v248, v248
	v_exp_f32_e32 v249, v249
	v_pk_add_f32 v[242:243], v[242:243], s[92:93]
	v_pk_add_f32 v[244:245], v[244:245], s[92:93]
	v_pk_add_f32 v[246:247], v[246:247], s[92:93]
	v_pk_add_f32 v[248:249], v[248:249], s[92:93]
	v_rcp_f32_e32 v242, v242
	v_rcp_f32_e32 v243, v243
	v_rcp_f32_e32 v244, v244
	v_rcp_f32_e32 v245, v245
	v_rcp_f32_e32 v246, v246
	v_rcp_f32_e32 v247, v247
	v_rcp_f32_e32 v248, v248
	v_rcp_f32_e32 v249, v249
	v_pk_mul_f32 v[202:203], v[202:203], v[242:243]
	v_pk_mul_f32 v[204:205], v[204:205], v[244:245]
	v_pk_mul_f32 v[206:207], v[206:207], v[246:247]
	v_pk_mul_f32 v[226:227], v[226:227], v[248:249]
	v_pk_mul_f32 v[18:19], v[18:19], v[202:203]
	v_pk_mul_f32 v[20:21], v[20:21], v[204:205]
	v_pk_mul_f32 v[10:11], v[10:11], v[206:207]
	v_pk_mul_f32 v[12:13], v[12:13], v[226:227]
	v_cvt_pk_bf16_f32 v250, v18, v19
	v_cvt_pk_bf16_f32 v251, v20, v21
	v_cvt_pk_bf16_f32 v252, v10, v11
	v_cvt_pk_bf16_f32 v253, v12, v13
	global_store_dwordx4 v175, v[250:253], s[72:73]
	s_add_u32 s72, s84, 0xf2000
	s_addc_u32 s73, s85, 0
	v_pk_mul_f32 v[202:203], v[86:87], v[78:79]
	v_pk_mul_f32 v[204:205], v[88:89], v[80:81]
	v_pk_mul_f32 v[206:207], v[146:147], v[82:83]
	v_pk_mul_f32 v[226:227], v[148:149], v[84:85]
	v_fmac_f32_dpp v202, v86, v26 row_shr:1 row_mask:0xf bank_mask:0xf bound_ctrl:1
	v_fmac_f32_dpp v203, v87, v27 row_shr:1 row_mask:0xf bank_mask:0xf bound_ctrl:1
	v_fmac_f32_dpp v204, v88, v28 row_shr:1 row_mask:0xf bank_mask:0xf bound_ctrl:1
	v_fmac_f32_dpp v205, v89, v29 row_shr:1 row_mask:0xf bank_mask:0xf bound_ctrl:1
	v_fmac_f32_dpp v206, v146, v74 row_shr:1 row_mask:0xf bank_mask:0xf bound_ctrl:1
	v_fmac_f32_dpp v207, v147, v75 row_shr:1 row_mask:0xf bank_mask:0xf bound_ctrl:1
	v_fmac_f32_dpp v226, v148, v76 row_shr:1 row_mask:0xf bank_mask:0xf bound_ctrl:1
	v_fmac_f32_dpp v227, v149, v77 row_shr:1 row_mask:0xf bank_mask:0xf bound_ctrl:1
	v_fmac_f32_dpp v202, v86, v14 row_shr:2 row_mask:0xf bank_mask:0xf bound_ctrl:1
	v_fmac_f32_dpp v203, v87, v15 row_shr:2 row_mask:0xf bank_mask:0xf bound_ctrl:1
	v_fmac_f32_dpp v204, v88, v16 row_shr:2 row_mask:0xf bank_mask:0xf bound_ctrl:1
	v_fmac_f32_dpp v205, v89, v17 row_shr:2 row_mask:0xf bank_mask:0xf bound_ctrl:1
	v_fmac_f32_dpp v206, v146, v22 row_shr:2 row_mask:0xf bank_mask:0xf bound_ctrl:1
	v_fmac_f32_dpp v207, v147, v23 row_shr:2 row_mask:0xf bank_mask:0xf bound_ctrl:1
	v_fmac_f32_dpp v226, v148, v24 row_shr:2 row_mask:0xf bank_mask:0xf bound_ctrl:1
	v_fmac_f32_dpp v227, v149, v25 row_shr:2 row_mask:0xf bank_mask:0xf bound_ctrl:1
	v_fmac_f32_dpp v202, v42, v154 row_ror:1 row_mask:0xf bank_mask:0xf bound_ctrl:1
	v_fmac_f32_dpp v203, v43, v155 row_ror:1 row_mask:0xf bank_mask:0xf bound_ctrl:1
	v_fmac_f32_dpp v204, v44, v156 row_ror:1 row_mask:0xf bank_mask:0xf bound_ctrl:1
	v_fmac_f32_dpp v205, v45, v157 row_ror:1 row_mask:0xf bank_mask:0xf bound_ctrl:1
	v_fmac_f32_dpp v206, v38, v158 row_ror:1 row_mask:0xf bank_mask:0xf bound_ctrl:1
	v_fmac_f32_dpp v207, v39, v159 row_ror:1 row_mask:0xf bank_mask:0xf bound_ctrl:1
	v_fmac_f32_dpp v226, v40, v160 row_ror:1 row_mask:0xf bank_mask:0xf bound_ctrl:1
	v_fmac_f32_dpp v227, v41, v161 row_ror:1 row_mask:0xf bank_mask:0xf bound_ctrl:1
	v_fmac_f32_dpp v202, v42, v182 row_ror:2 row_mask:0xf bank_mask:0xf bound_ctrl:1
	v_fmac_f32_dpp v203, v43, v183 row_ror:2 row_mask:0xf bank_mask:0xf bound_ctrl:1
	v_fmac_f32_dpp v204, v44, v184 row_ror:2 row_mask:0xf bank_mask:0xf bound_ctrl:1
	v_fmac_f32_dpp v205, v45, v185 row_ror:2 row_mask:0xf bank_mask:0xf bound_ctrl:1
	v_fmac_f32_dpp v206, v38, v190 row_ror:2 row_mask:0xf bank_mask:0xf bound_ctrl:1
	v_fmac_f32_dpp v207, v39, v191 row_ror:2 row_mask:0xf bank_mask:0xf bound_ctrl:1
	v_fmac_f32_dpp v226, v40, v192 row_ror:2 row_mask:0xf bank_mask:0xf bound_ctrl:1
	v_fmac_f32_dpp v227, v41, v193 row_ror:2 row_mask:0xf bank_mask:0xf bound_ctrl:1
	v_pk_mul_f32 v[242:243], v[202:203], s[98:99]
	v_pk_mul_f32 v[244:245], v[204:205], s[98:99]
	v_pk_mul_f32 v[246:247], v[206:207], s[98:99]
	v_pk_mul_f32 v[248:249], v[226:227], s[98:99]
	v_exp_f32_e32 v242, v242
	v_exp_f32_e32 v243, v243
	v_exp_f32_e32 v244, v244
	v_exp_f32_e32 v245, v245
	v_exp_f32_e32 v246, v246
	v_exp_f32_e32 v247, v247
	v_exp_f32_e32 v248, v248
	v_exp_f32_e32 v249, v249
	v_pk_add_f32 v[242:243], v[242:243], s[92:93]
	v_pk_add_f32 v[244:245], v[244:245], s[92:93]
	v_pk_add_f32 v[246:247], v[246:247], s[92:93]
	v_pk_add_f32 v[248:249], v[248:249], s[92:93]
	v_rcp_f32_e32 v242, v242
	v_rcp_f32_e32 v243, v243
	v_rcp_f32_e32 v244, v244
	v_rcp_f32_e32 v245, v245
	v_rcp_f32_e32 v246, v246
	v_rcp_f32_e32 v247, v247
	v_rcp_f32_e32 v248, v248
	v_rcp_f32_e32 v249, v249
	v_pk_mul_f32 v[202:203], v[202:203], v[242:243]
	v_pk_mul_f32 v[204:205], v[204:205], v[244:245]
	v_pk_mul_f32 v[206:207], v[206:207], v[246:247]
	v_pk_mul_f32 v[226:227], v[226:227], v[248:249]
	v_pk_mul_f32 v[6:7], v[6:7], v[202:203]
	v_pk_mul_f32 v[8:9], v[8:9], v[204:205]
	v_pk_mul_f32 v[2:3], v[2:3], v[206:207]
	v_pk_mul_f32 v[4:5], v[4:5], v[226:227]
	v_cvt_pk_bf16_f32 v250, v6, v7
	v_cvt_pk_bf16_f32 v251, v8, v9
	v_cvt_pk_bf16_f32 v252, v2, v3
	v_cvt_pk_bf16_f32 v253, v4, v5
	global_store_dwordx4 v175, v[250:253], s[72:73]
	s_andn2_b64 vcc, exec, s[38:39]
	s_mov_b64 s[38:39], -1
	s_cbranch_vccnz .LBB0_239
	s_andn2_b64 vcc, exec, s[62:63]
	s_cbranch_vccnz .LBB0_238
	s_barrier
	s_branch .LBB0_238
